# MoE GEMM epilogues: token indices (list) of the four 16-row groups fetched together at the epilogue entry, then the four gate weights (tokw) together; one vmcnt wait instead of 8 (moe1) / 4 (moe2) dep
# speedup vs baseline: 1.0439x; 1.0003x over previous
.LBB0_723:
	v_add_u32_e32 v252, -1, v142
	v_add_u32_e32 v244, v139, v157
	v_add3_u32 v246, v139, v157, 16
	v_add3_u32 v248, v139, v157, 32
	v_add3_u32 v250, v139, v157, 48
	v_readlane_b32 s100, v237, 42
	v_readlane_b32 s101, v237, 43
	v_min_i32_e32 v244, v244, v252
	v_min_i32_e32 v246, v246, v252
	v_min_i32_e32 v248, v248, v252
	v_min_i32_e32 v250, v250, v252
	v_mov_b32_e32 v245, 0
	v_mov_b32_e32 v247, 0
	v_mov_b32_e32 v249, 0
	v_mov_b32_e32 v251, 0
	v_mov_b32_e32 v254, v132
	v_mov_b32_e32 v255, 0
	v_lshlrev_b64 v[254:255], 17, v[254:255]
	v_lshl_add_u64 v[254:255], s[100:101], 0, v[254:255]
	v_lshl_add_u64 v[244:245], v[244:245], 2, v[254:255]
	v_lshl_add_u64 v[246:247], v[246:247], 2, v[254:255]
	v_lshl_add_u64 v[248:249], v[248:249], 2, v[254:255]
	v_lshl_add_u64 v[250:251], v[250:251], 2, v[254:255]
	global_load_dword v240, v[244:245], off
	global_load_dword v241, v[246:247], off
	global_load_dword v242, v[248:249], off
	global_load_dword v243, v[250:251], off
	v_readlane_b32 s100, v237, 44
	v_readlane_b32 s101, v237, 45
	s_and_b32 s98, s82, 4
	s_mov_b32 s99, 0
	s_waitcnt vmcnt(0)
	v_mov_b32_e32 v244, v240
	v_mov_b32_e32 v245, 0
	v_mov_b32_e32 v246, v241
	v_mov_b32_e32 v247, 0
	v_mov_b32_e32 v248, v242
	v_mov_b32_e32 v249, 0
	v_mov_b32_e32 v250, v243
	v_mov_b32_e32 v251, 0
	v_lshl_add_u64 v[244:245], v[244:245], 3, s[100:101]
	v_lshl_add_u64 v[246:247], v[246:247], 3, s[100:101]
	v_lshl_add_u64 v[248:249], v[248:249], 3, s[100:101]
	v_lshl_add_u64 v[250:251], v[250:251], 3, s[100:101]
	v_lshl_add_u64 v[244:245], v[244:245], 0, s[98:99]
	v_lshl_add_u64 v[246:247], v[246:247], 0, s[98:99]
	v_lshl_add_u64 v[248:249], v[248:249], 0, s[98:99]
	v_lshl_add_u64 v[250:251], v[250:251], 0, s[98:99]
	global_load_dword v252, v[244:245], off
	global_load_dword v253, v[246:247], off
	global_load_dword v254, v[248:249], off
	global_load_dword v255, v[250:251], off
	s_lshl_b32 s0, s82, 1
	v_and_or_b32 v130, s0, 6, v138
	v_lshlrev_b32_e32 v130, 5, v130
	v_lshlrev_b32_e32 v133, 2, v140
	v_add_u32_e32 v140, v157, v139
	s_and_b32 s6, s82, 7
	v_cmp_lt_i32_e32 vcc, v140, v142
	v_lshlrev_b32_e32 v130, 1, v130
	v_lshlrev_b32_e32 v136, 1, v133
	s_and_saveexec_b64 s[0:1], vcc
	s_cbranch_execz .LBB0_725
	v_mov_b32_e32 v133, v131
	v_readlane_b32 s4, v237, 42
	v_lshlrev_b64 v[158:159], 17, v[132:133]
	v_readlane_b32 s5, v237, 43
	v_ashrrev_i32_e32 v141, 31, v140
	s_and_b32 s2, s6, 4
	v_lshl_add_u64 v[158:159], s[4:5], 0, v[158:159]
	v_lshl_add_u64 v[158:159], v[140:141], 2, v[158:159]
	v_readlane_b32 s4, v237, 44
	v_readlane_b32 s5, v237, 45
	v_mul_f32_e32 v133, 0xbfb8aa3b, v124
	v_exp_f32_e32 v133, v133
	v_mov_b32_e32 v137, v131
	v_add_f32_e32 v133, 1.0, v133
	v_ashrrev_i32_e32 v159, 31, v158
	v_lshl_add_u64 v[158:159], v[158:159], 3, s[4:5]
	v_lshl_add_u64 v[158:159], v[158:159], 0, s[2:3]
	v_rcp_f32_e32 v158, v133
	v_mul_f32_e32 v133, 0xbfb8aa3b, v125
	v_exp_f32_e32 v133, v133
	s_lshl_b32 s2, s6, 7
	s_and_b32 s2, s2, 0x200
	v_add_f32_e32 v133, 1.0, v133
	v_rcp_f32_e32 v159, v133
	s_nop 0
	v_pk_mul_f32 v[124:125], v[124:125], v[158:159]
	s_nop 0
	v_pk_mul_f32 v[120:121], v[124:125], v[120:121]
	v_mul_f32_e32 v124, 0xbfb8aa3b, v126
	v_mul_f32_e32 v125, 0xbfb8aa3b, v127
	v_exp_f32_e32 v124, v124
	v_exp_f32_e32 v125, v125
	v_add_f32_e32 v124, 1.0, v124
	v_add_f32_e32 v125, 1.0, v125
	v_rcp_f32_e32 v124, v124
	v_rcp_f32_e32 v125, v125
	s_waitcnt vmcnt(0)
	v_mov_b32_e32 v138, v252
	v_pk_mul_f32 v[120:121], v[120:121], v[138:139] op_sel_hi:[1,0]
	v_pk_mul_f32 v[124:125], v[126:127], v[124:125]
	v_cvt_pk_bf16_f32 v120, v120, v121
	v_pk_mul_f32 v[122:123], v[124:125], v[122:123]
	s_nop 0
	v_pk_mul_f32 v[122:123], v[122:123], v[138:139] op_sel_hi:[1,0]
	s_nop 0
	v_cvt_pk_bf16_f32 v121, v122, v123
	v_add_u32_e32 v122, v140, v143
	v_ashrrev_i32_e32 v123, 31, v122
	v_lshlrev_b64 v[122:123], 10, v[122:123]
	v_lshl_add_u64 v[122:123], s[88:89], 0, v[122:123]
	v_lshl_add_u64 v[122:123], v[122:123], 0, s[2:3]
	v_lshl_add_u64 v[122:123], v[122:123], 0, v[130:131]
	v_lshl_add_u64 v[122:123], v[122:123], 0, v[136:137]
	global_store_dwordx2 v[122:123], v[120:121], off
	v_mul_f32_e32 v120, 0xbfb8aa3b, v116
	v_mul_f32_e32 v121, 0xbfb8aa3b, v117
	v_exp_f32_e32 v120, v120
	v_exp_f32_e32 v121, v121
	v_add_f32_e32 v120, 1.0, v120
	v_add_f32_e32 v121, 1.0, v121
	v_rcp_f32_e32 v120, v120
	v_rcp_f32_e32 v121, v121
	s_nop 0
	v_pk_mul_f32 v[116:117], v[116:117], v[120:121]
	s_nop 0
	v_pk_mul_f32 v[112:113], v[116:117], v[112:113]
	v_mul_f32_e32 v116, 0xbfb8aa3b, v118
	v_mul_f32_e32 v117, 0xbfb8aa3b, v119
	v_exp_f32_e32 v116, v116
	v_exp_f32_e32 v117, v117
	v_pk_mul_f32 v[112:113], v[112:113], v[138:139] op_sel_hi:[1,0]
	v_add_f32_e32 v116, 1.0, v116
	v_add_f32_e32 v117, 1.0, v117
	v_rcp_f32_e32 v116, v116
	v_rcp_f32_e32 v117, v117
	v_cvt_pk_bf16_f32 v112, v112, v113
	v_pk_mul_f32 v[116:117], v[118:119], v[116:117]
	s_nop 0
	v_pk_mul_f32 v[114:115], v[116:117], v[114:115]
	s_nop 0
	v_pk_mul_f32 v[114:115], v[114:115], v[138:139] op_sel_hi:[1,0]
	s_nop 0
	v_cvt_pk_bf16_f32 v113, v114, v115
	global_store_dwordx2 v[122:123], v[112:113], off offset:32
.LBB0_725:
	s_or_b64 exec, exec, s[0:1]
	v_add3_u32 v114, v139, v157, 16
	v_cmp_lt_i32_e32 vcc, v114, v142
	s_and_saveexec_b64 s[0:1], vcc
	s_cbranch_execz .LBB0_727
	v_mov_b32_e32 v133, v131
	v_readlane_b32 s4, v237, 42
	v_lshlrev_b64 v[112:113], 17, v[132:133]
	v_readlane_b32 s5, v237, 43
	v_ashrrev_i32_e32 v115, 31, v114
	s_and_b32 s2, s6, 4
	v_lshl_add_u64 v[112:113], s[4:5], 0, v[112:113]
	v_lshl_add_u64 v[112:113], v[114:115], 2, v[112:113]
	v_readlane_b32 s4, v237, 44
	v_readlane_b32 s5, v237, 45
	v_mov_b32_e32 v137, v131
	v_ashrrev_i32_e32 v113, 31, v112
	v_lshl_add_u64 v[112:113], v[112:113], 3, s[4:5]
	v_lshl_add_u64 v[112:113], v[112:113], 0, s[2:3]
	v_mul_f32_e32 v113, 0xbfb8aa3b, v108
	v_exp_f32_e32 v113, v113
	s_lshl_b32 s2, s6, 7
	s_and_b32 s2, s2, 0x200
	v_add_f32_e32 v113, 1.0, v113
	v_rcp_f32_e32 v116, v113
	v_mul_f32_e32 v113, 0xbfb8aa3b, v109
	v_exp_f32_e32 v113, v113
	s_nop 0
	v_add_f32_e32 v113, 1.0, v113
	v_rcp_f32_e32 v117, v113
	s_nop 0
	v_pk_mul_f32 v[108:109], v[108:109], v[116:117]
	s_nop 0
	v_pk_mul_f32 v[104:105], v[108:109], v[104:105]
	v_mul_f32_e32 v108, 0xbfb8aa3b, v110
	v_mul_f32_e32 v109, 0xbfb8aa3b, v111
	v_exp_f32_e32 v108, v108
	v_exp_f32_e32 v109, v109
	v_add_f32_e32 v108, 1.0, v108
	v_add_f32_e32 v109, 1.0, v109
	v_rcp_f32_e32 v108, v108
	v_rcp_f32_e32 v109, v109
	v_mov_b32_e32 v112, v253
	v_pk_mul_f32 v[104:105], v[104:105], v[112:113] op_sel_hi:[1,0]
	v_pk_mul_f32 v[108:109], v[110:111], v[108:109]
	v_cvt_pk_bf16_f32 v104, v104, v105
	v_pk_mul_f32 v[106:107], v[108:109], v[106:107]
	s_nop 0
	v_pk_mul_f32 v[106:107], v[106:107], v[112:113] op_sel_hi:[1,0]
	s_nop 0
	v_cvt_pk_bf16_f32 v105, v106, v107
	v_add_u32_e32 v106, v114, v143
	v_ashrrev_i32_e32 v107, 31, v106
	v_lshlrev_b64 v[106:107], 10, v[106:107]
	v_lshl_add_u64 v[106:107], s[88:89], 0, v[106:107]
	v_lshl_add_u64 v[106:107], v[106:107], 0, s[2:3]
	v_lshl_add_u64 v[106:107], v[106:107], 0, v[130:131]
	v_lshl_add_u64 v[106:107], v[106:107], 0, v[136:137]
	global_store_dwordx2 v[106:107], v[104:105], off
	v_mul_f32_e32 v104, 0xbfb8aa3b, v100
	v_mul_f32_e32 v105, 0xbfb8aa3b, v101
	v_exp_f32_e32 v104, v104
	v_exp_f32_e32 v105, v105
	v_add_f32_e32 v104, 1.0, v104
	v_add_f32_e32 v105, 1.0, v105
	v_rcp_f32_e32 v104, v104
	v_rcp_f32_e32 v105, v105
	s_nop 0
	v_pk_mul_f32 v[100:101], v[100:101], v[104:105]
	s_nop 0
	v_pk_mul_f32 v[96:97], v[100:101], v[96:97]
	v_mul_f32_e32 v100, 0xbfb8aa3b, v102
	v_mul_f32_e32 v101, 0xbfb8aa3b, v103
	v_exp_f32_e32 v100, v100
	v_exp_f32_e32 v101, v101
	v_pk_mul_f32 v[96:97], v[96:97], v[112:113] op_sel_hi:[1,0]
	v_add_f32_e32 v100, 1.0, v100
	v_add_f32_e32 v101, 1.0, v101
	v_rcp_f32_e32 v100, v100
	v_rcp_f32_e32 v101, v101
	v_cvt_pk_bf16_f32 v96, v96, v97
	v_pk_mul_f32 v[100:101], v[102:103], v[100:101]
	s_nop 0
	v_pk_mul_f32 v[98:99], v[100:101], v[98:99]
	s_nop 0
	v_pk_mul_f32 v[98:99], v[98:99], v[112:113] op_sel_hi:[1,0]
	s_nop 0
	v_cvt_pk_bf16_f32 v97, v98, v99
	global_store_dwordx2 v[106:107], v[96:97], off offset:32
.LBB0_727:
	s_or_b64 exec, exec, s[0:1]
	v_add3_u32 v98, v139, v157, 32
	v_cmp_lt_i32_e32 vcc, v98, v142
	s_and_saveexec_b64 s[0:1], vcc
	s_cbranch_execz .LBB0_729
	v_mov_b32_e32 v133, v131
	v_readlane_b32 s4, v237, 42
	v_lshlrev_b64 v[96:97], 17, v[132:133]
	v_readlane_b32 s5, v237, 43
	v_ashrrev_i32_e32 v99, 31, v98
	s_and_b32 s2, s6, 4
	v_lshl_add_u64 v[96:97], s[4:5], 0, v[96:97]
	v_lshl_add_u64 v[96:97], v[98:99], 2, v[96:97]
	v_readlane_b32 s4, v237, 44
	v_readlane_b32 s5, v237, 45
	v_mov_b32_e32 v137, v131
	v_ashrrev_i32_e32 v97, 31, v96
	v_lshl_add_u64 v[96:97], v[96:97], 3, s[4:5]
	v_lshl_add_u64 v[96:97], v[96:97], 0, s[2:3]
	v_mul_f32_e32 v97, 0xbfb8aa3b, v92
	v_exp_f32_e32 v97, v97
	s_lshl_b32 s2, s6, 7
	s_and_b32 s2, s2, 0x200
	v_add_f32_e32 v97, 1.0, v97
	v_rcp_f32_e32 v100, v97
	v_mul_f32_e32 v97, 0xbfb8aa3b, v93
	v_exp_f32_e32 v97, v97
	s_nop 0
	v_add_f32_e32 v97, 1.0, v97
	v_rcp_f32_e32 v101, v97
	s_nop 0
	v_pk_mul_f32 v[92:93], v[92:93], v[100:101]
	s_nop 0
	v_pk_mul_f32 v[88:89], v[92:93], v[88:89]
	v_mul_f32_e32 v92, 0xbfb8aa3b, v94
	v_mul_f32_e32 v93, 0xbfb8aa3b, v95
	v_exp_f32_e32 v92, v92
	v_exp_f32_e32 v93, v93
	v_add_f32_e32 v92, 1.0, v92
	v_add_f32_e32 v93, 1.0, v93
	v_rcp_f32_e32 v92, v92
	v_rcp_f32_e32 v93, v93
	v_mov_b32_e32 v96, v254
	v_pk_mul_f32 v[88:89], v[88:89], v[96:97] op_sel_hi:[1,0]
	v_pk_mul_f32 v[92:93], v[94:95], v[92:93]
	v_cvt_pk_bf16_f32 v88, v88, v89
	v_pk_mul_f32 v[90:91], v[92:93], v[90:91]
	s_nop 0
	v_pk_mul_f32 v[90:91], v[90:91], v[96:97] op_sel_hi:[1,0]
	s_nop 0
	v_cvt_pk_bf16_f32 v89, v90, v91
	v_add_u32_e32 v90, v98, v143
	v_ashrrev_i32_e32 v91, 31, v90
	v_lshlrev_b64 v[90:91], 10, v[90:91]
	v_lshl_add_u64 v[90:91], s[88:89], 0, v[90:91]
	v_lshl_add_u64 v[90:91], v[90:91], 0, s[2:3]
	v_lshl_add_u64 v[90:91], v[90:91], 0, v[130:131]
	v_lshl_add_u64 v[90:91], v[90:91], 0, v[136:137]
	global_store_dwordx2 v[90:91], v[88:89], off
	v_mul_f32_e32 v88, 0xbfb8aa3b, v84
	v_mul_f32_e32 v89, 0xbfb8aa3b, v85
	v_exp_f32_e32 v88, v88
	v_exp_f32_e32 v89, v89
	v_add_f32_e32 v88, 1.0, v88
	v_add_f32_e32 v89, 1.0, v89
	v_rcp_f32_e32 v88, v88
	v_rcp_f32_e32 v89, v89
	s_nop 0
	v_pk_mul_f32 v[84:85], v[84:85], v[88:89]
	s_nop 0
	v_pk_mul_f32 v[80:81], v[84:85], v[80:81]
	v_mul_f32_e32 v84, 0xbfb8aa3b, v86
	v_mul_f32_e32 v85, 0xbfb8aa3b, v87
	v_exp_f32_e32 v84, v84
	v_exp_f32_e32 v85, v85
	v_pk_mul_f32 v[80:81], v[80:81], v[96:97] op_sel_hi:[1,0]
	v_add_f32_e32 v84, 1.0, v84
	v_add_f32_e32 v85, 1.0, v85
	v_rcp_f32_e32 v84, v84
	v_rcp_f32_e32 v85, v85
	v_cvt_pk_bf16_f32 v80, v80, v81
	v_pk_mul_f32 v[84:85], v[86:87], v[84:85]
	s_nop 0
	v_pk_mul_f32 v[82:83], v[84:85], v[82:83]
	s_nop 0
	v_pk_mul_f32 v[82:83], v[82:83], v[96:97] op_sel_hi:[1,0]
	s_nop 0
	v_cvt_pk_bf16_f32 v81, v82, v83
	global_store_dwordx2 v[90:91], v[80:81], off offset:32
.LBB0_729:
	s_or_b64 exec, exec, s[0:1]
	v_add3_u32 v82, v139, v157, 48
	v_cmp_lt_i32_e32 vcc, v82, v142
	s_and_saveexec_b64 s[0:1], vcc
	s_cbranch_execz .LBB0_731
	v_mov_b32_e32 v133, v131
	v_readlane_b32 s4, v237, 42
	v_lshlrev_b64 v[80:81], 17, v[132:133]
	v_readlane_b32 s5, v237, 43
	v_ashrrev_i32_e32 v83, 31, v82
	s_and_b32 s2, s6, 4
	v_lshl_add_u64 v[80:81], s[4:5], 0, v[80:81]
	v_lshl_add_u64 v[80:81], v[82:83], 2, v[80:81]
	v_readlane_b32 s4, v237, 44
	v_readlane_b32 s5, v237, 45
	v_mov_b32_e32 v137, v131
	v_ashrrev_i32_e32 v81, 31, v80
	v_lshl_add_u64 v[80:81], v[80:81], 3, s[4:5]
	v_lshl_add_u64 v[80:81], v[80:81], 0, s[2:3]
	v_mul_f32_e32 v81, 0xbfb8aa3b, v76
	v_exp_f32_e32 v81, v81
	s_lshl_b32 s2, s6, 7
	s_and_b32 s2, s2, 0x200
	v_add_f32_e32 v81, 1.0, v81
	v_rcp_f32_e32 v84, v81
	v_mul_f32_e32 v81, 0xbfb8aa3b, v77
	v_exp_f32_e32 v81, v81
	s_nop 0
	v_add_f32_e32 v81, 1.0, v81
	v_rcp_f32_e32 v85, v81
	s_nop 0
	v_pk_mul_f32 v[76:77], v[76:77], v[84:85]
	s_nop 0
	v_pk_mul_f32 v[72:73], v[76:77], v[72:73]
	v_mul_f32_e32 v76, 0xbfb8aa3b, v78
	v_mul_f32_e32 v77, 0xbfb8aa3b, v79
	v_exp_f32_e32 v76, v76
	v_exp_f32_e32 v77, v77
	v_add_f32_e32 v76, 1.0, v76
	v_add_f32_e32 v77, 1.0, v77
	v_rcp_f32_e32 v76, v76
	v_rcp_f32_e32 v77, v77
	v_mov_b32_e32 v80, v255
	v_pk_mul_f32 v[72:73], v[72:73], v[80:81] op_sel_hi:[1,0]
	v_pk_mul_f32 v[76:77], v[78:79], v[76:77]
	v_cvt_pk_bf16_f32 v72, v72, v73
	v_pk_mul_f32 v[74:75], v[76:77], v[74:75]
	s_nop 0
	v_pk_mul_f32 v[74:75], v[74:75], v[80:81] op_sel_hi:[1,0]
	s_nop 0
	v_cvt_pk_bf16_f32 v73, v74, v75
	v_add_u32_e32 v74, v82, v143
	v_ashrrev_i32_e32 v75, 31, v74
	v_lshlrev_b64 v[74:75], 10, v[74:75]
	v_lshl_add_u64 v[74:75], s[88:89], 0, v[74:75]
	v_lshl_add_u64 v[74:75], v[74:75], 0, s[2:3]
	v_lshl_add_u64 v[74:75], v[74:75], 0, v[130:131]
	v_lshl_add_u64 v[74:75], v[74:75], 0, v[136:137]
	global_store_dwordx2 v[74:75], v[72:73], off
	v_mul_f32_e32 v72, 0xbfb8aa3b, v68
	v_mul_f32_e32 v73, 0xbfb8aa3b, v69
	v_exp_f32_e32 v72, v72
	v_exp_f32_e32 v73, v73
	v_add_f32_e32 v72, 1.0, v72
	v_add_f32_e32 v73, 1.0, v73
	v_rcp_f32_e32 v72, v72
	v_rcp_f32_e32 v73, v73
	s_nop 0
	v_pk_mul_f32 v[68:69], v[68:69], v[72:73]
	s_nop 0
	v_pk_mul_f32 v[64:65], v[68:69], v[64:65]
	v_mul_f32_e32 v68, 0xbfb8aa3b, v70
	v_mul_f32_e32 v69, 0xbfb8aa3b, v71
	v_exp_f32_e32 v68, v68
	v_exp_f32_e32 v69, v69
	v_pk_mul_f32 v[64:65], v[64:65], v[80:81] op_sel_hi:[1,0]
	v_add_f32_e32 v68, 1.0, v68
	v_add_f32_e32 v69, 1.0, v69
	v_rcp_f32_e32 v68, v68
	v_rcp_f32_e32 v69, v69
	v_cvt_pk_bf16_f32 v64, v64, v65
	v_pk_mul_f32 v[68:69], v[70:71], v[68:69]
	s_nop 0
	v_pk_mul_f32 v[66:67], v[68:69], v[66:67]
	s_nop 0
	v_pk_mul_f32 v[66:67], v[66:67], v[80:81] op_sel_hi:[1,0]
	s_nop 0
	v_cvt_pk_bf16_f32 v65, v66, v67
	global_store_dwordx2 v[74:75], v[64:65], off offset:32
	s_or_b64 exec, exec, s[0:1]
	s_andn2_b64 vcc, exec, s[10:11]
	s_cbranch_vccnz .LBB0_673
	s_branch .LBB0_732

.LBB0_863:
	v_add_u32_e32 v252, -1, v139
	v_add_u32_e32 v244, v138, v154
	v_add3_u32 v246, v138, v154, 16
	v_add3_u32 v248, v138, v154, 32
	v_add3_u32 v250, v138, v154, 48
	v_readlane_b32 s100, v237, 42
	v_readlane_b32 s101, v237, 43
	v_min_i32_e32 v244, v244, v252
	v_min_i32_e32 v246, v246, v252
	v_min_i32_e32 v248, v248, v252
	v_min_i32_e32 v250, v250, v252
	v_mov_b32_e32 v245, 0
	v_mov_b32_e32 v247, 0
	v_mov_b32_e32 v249, 0
	v_mov_b32_e32 v251, 0
	v_mov_b32_e32 v254, v130
	v_mov_b32_e32 v255, 0
	v_lshlrev_b64 v[254:255], 17, v[254:255]
	v_lshl_add_u64 v[254:255], s[100:101], 0, v[254:255]
	v_lshl_add_u64 v[244:245], v[244:245], 2, v[254:255]
	v_lshl_add_u64 v[246:247], v[246:247], 2, v[254:255]
	v_lshl_add_u64 v[248:249], v[248:249], 2, v[254:255]
	v_lshl_add_u64 v[250:251], v[250:251], 2, v[254:255]
	global_load_dword v240, v[244:245], off
	global_load_dword v241, v[246:247], off
	global_load_dword v242, v[248:249], off
	global_load_dword v243, v[250:251], off
	v_and_b32_e32 v131, 64, v131
	v_lshlrev_b32_e32 v134, 2, v159
	v_add_u32_e32 v136, v154, v138
	s_and_b32 s4, s16, 7
	v_cmp_lt_i32_e32 vcc, v136, v139
	v_lshlrev_b32_e32 v132, 1, v131
	v_lshlrev_b32_e32 v134, 1, v134
	s_and_saveexec_b64 s[0:1], vcc
	s_cbranch_execz .LBB0_865
	v_mov_b32_e32 v131, v133
	v_readlane_b32 s14, v237, 42
	v_lshlrev_b64 v[148:149], 17, v[130:131]
	v_readlane_b32 s15, v237, 43
	v_ashrrev_i32_e32 v137, 31, v136
	v_cvt_pk_bf16_f32 v112, v112, v113
	v_lshl_add_u64 v[148:149], s[14:15], 0, v[148:149]
	v_lshl_add_u64 v[136:137], v[136:137], 2, v[148:149]
	v_readlane_b32 s14, v237, 40
	v_cvt_pk_bf16_f32 v113, v114, v115
	v_readlane_b32 s15, v237, 41
	s_lshl_b32 s2, s4, 8
	v_mov_b32_e32 v135, v133
	v_cvt_pk_bf16_f32 v124, v124, v125
	v_cvt_pk_bf16_f32 v125, v126, v127
	v_cvt_pk_bf16_f32 v120, v120, v121
	v_cvt_pk_bf16_f32 v121, v122, v123
	v_cvt_pk_bf16_f32 v116, v116, v117
	v_cvt_pk_bf16_f32 v117, v118, v119
	s_waitcnt vmcnt(0)
	v_mov_b32_e32 v136, v240
	v_ashrrev_i32_e32 v137, 31, v136
	v_lshlrev_b64 v[114:115], 11, v[136:137]
	v_lshl_add_u64 v[114:115], s[14:15], 0, v[114:115]
	v_lshl_add_u64 v[114:115], v[114:115], 0, s[2:3]
	v_lshl_add_u64 v[114:115], v[114:115], 0, v[132:133]
	v_lshl_add_u64 v[114:115], v[114:115], 0, v[134:135]
	global_store_dwordx2 v[114:115], v[124:125], off
	global_store_dwordx2 v[114:115], v[120:121], off offset:32
	global_store_dwordx2 v[114:115], v[116:117], off offset:64
	global_store_dwordx2 v[114:115], v[112:113], off offset:96
.LBB0_865:
	s_or_b64 exec, exec, s[0:1]
	v_add3_u32 v112, v138, v154, 16
	v_cmp_lt_i32_e32 vcc, v112, v139
	s_and_saveexec_b64 s[0:1], vcc
	s_cbranch_execz .LBB0_867
	v_mov_b32_e32 v131, v133
	v_readlane_b32 s14, v237, 42
	v_lshlrev_b64 v[114:115], 17, v[130:131]
	v_readlane_b32 s15, v237, 43
	v_ashrrev_i32_e32 v113, 31, v112
	v_cvt_pk_bf16_f32 v96, v96, v97
	v_lshl_add_u64 v[114:115], s[14:15], 0, v[114:115]
	v_lshl_add_u64 v[112:113], v[112:113], 2, v[114:115]
	v_readlane_b32 s14, v237, 40
	v_cvt_pk_bf16_f32 v97, v98, v99
	v_readlane_b32 s15, v237, 41
	s_lshl_b32 s2, s4, 8
	v_mov_b32_e32 v135, v133
	v_cvt_pk_bf16_f32 v108, v108, v109
	v_cvt_pk_bf16_f32 v109, v110, v111
	v_cvt_pk_bf16_f32 v104, v104, v105
	v_cvt_pk_bf16_f32 v105, v106, v107
	v_cvt_pk_bf16_f32 v100, v100, v101
	v_cvt_pk_bf16_f32 v101, v102, v103
	v_mov_b32_e32 v112, v241
	v_ashrrev_i32_e32 v113, 31, v112
	v_lshlrev_b64 v[98:99], 11, v[112:113]
	v_lshl_add_u64 v[98:99], s[14:15], 0, v[98:99]
	v_lshl_add_u64 v[98:99], v[98:99], 0, s[2:3]
	v_lshl_add_u64 v[98:99], v[98:99], 0, v[132:133]
	v_lshl_add_u64 v[98:99], v[98:99], 0, v[134:135]
	global_store_dwordx2 v[98:99], v[108:109], off
	global_store_dwordx2 v[98:99], v[104:105], off offset:32
	global_store_dwordx2 v[98:99], v[100:101], off offset:64
	global_store_dwordx2 v[98:99], v[96:97], off offset:96
.LBB0_867:
	s_or_b64 exec, exec, s[0:1]
	v_add3_u32 v96, v138, v154, 32
	v_cmp_lt_i32_e32 vcc, v96, v139
	s_and_saveexec_b64 s[0:1], vcc
	s_cbranch_execz .LBB0_869
	v_mov_b32_e32 v131, v133
	v_readlane_b32 s14, v237, 42
	v_lshlrev_b64 v[98:99], 17, v[130:131]
	v_readlane_b32 s15, v237, 43
	v_ashrrev_i32_e32 v97, 31, v96
	v_cvt_pk_bf16_f32 v80, v80, v81
	v_lshl_add_u64 v[98:99], s[14:15], 0, v[98:99]
	v_lshl_add_u64 v[96:97], v[96:97], 2, v[98:99]
	v_readlane_b32 s14, v237, 40
	v_cvt_pk_bf16_f32 v81, v82, v83
	v_readlane_b32 s15, v237, 41
	s_lshl_b32 s2, s4, 8
	v_mov_b32_e32 v135, v133
	v_cvt_pk_bf16_f32 v92, v92, v93
	v_cvt_pk_bf16_f32 v93, v94, v95
	v_cvt_pk_bf16_f32 v88, v88, v89
	v_cvt_pk_bf16_f32 v89, v90, v91
	v_cvt_pk_bf16_f32 v84, v84, v85
	v_cvt_pk_bf16_f32 v85, v86, v87
	v_mov_b32_e32 v96, v242
	v_ashrrev_i32_e32 v97, 31, v96
	v_lshlrev_b64 v[82:83], 11, v[96:97]
	v_lshl_add_u64 v[82:83], s[14:15], 0, v[82:83]
	v_lshl_add_u64 v[82:83], v[82:83], 0, s[2:3]
	v_lshl_add_u64 v[82:83], v[82:83], 0, v[132:133]
	v_lshl_add_u64 v[82:83], v[82:83], 0, v[134:135]
	global_store_dwordx2 v[82:83], v[92:93], off
	global_store_dwordx2 v[82:83], v[88:89], off offset:32
	global_store_dwordx2 v[82:83], v[84:85], off offset:64
	global_store_dwordx2 v[82:83], v[80:81], off offset:96
.LBB0_869:
	s_or_b64 exec, exec, s[0:1]
	v_add3_u32 v80, v138, v154, 48
	v_cmp_lt_i32_e32 vcc, v80, v139
	s_and_saveexec_b64 s[0:1], vcc
	s_cbranch_execz .LBB0_871
	v_mov_b32_e32 v131, v133
	v_readlane_b32 s14, v237, 42
	v_lshlrev_b64 v[82:83], 17, v[130:131]
	v_readlane_b32 s15, v237, 43
	v_ashrrev_i32_e32 v81, 31, v80
	s_lshl_b32 s2, s4, 8
	v_lshl_add_u64 v[82:83], s[14:15], 0, v[82:83]
	v_lshl_add_u64 v[80:81], v[80:81], 2, v[82:83]
	v_readlane_b32 s4, v237, 40
	v_cvt_pk_bf16_f32 v64, v64, v65
	v_cvt_pk_bf16_f32 v65, v66, v67
	v_readlane_b32 s5, v237, 41
	v_mov_b32_e32 v135, v133
	v_cvt_pk_bf16_f32 v76, v76, v77
	v_cvt_pk_bf16_f32 v77, v78, v79
	v_cvt_pk_bf16_f32 v72, v72, v73
	v_cvt_pk_bf16_f32 v73, v74, v75
	v_cvt_pk_bf16_f32 v68, v68, v69
	v_cvt_pk_bf16_f32 v69, v70, v71
	v_mov_b32_e32 v80, v243
	v_ashrrev_i32_e32 v81, 31, v80
	v_lshlrev_b64 v[66:67], 11, v[80:81]
	v_lshl_add_u64 v[66:67], s[4:5], 0, v[66:67]
	v_lshl_add_u64 v[66:67], v[66:67], 0, s[2:3]
	v_lshl_add_u64 v[66:67], v[66:67], 0, v[132:133]
	v_lshl_add_u64 v[66:67], v[66:67], 0, v[134:135]
	global_store_dwordx2 v[66:67], v[76:77], off
	global_store_dwordx2 v[66:67], v[72:73], off offset:32
	global_store_dwordx2 v[66:67], v[68:69], off offset:64
	global_store_dwordx2 v[66:67], v[64:65], off offset:96
	s_or_b64 exec, exec, s[0:1]
	s_andn2_b64 vcc, exec, s[10:11]
	s_cbranch_vccnz .LBB0_813
	s_branch .LBB0_872

.LBB0_1847:
	v_add_u32_e32 v252, -1, v141
	v_add_u32_e32 v244, v140, v156
	v_add3_u32 v246, v140, v156, 16
	v_add3_u32 v248, v140, v156, 32
	v_add3_u32 v250, v140, v156, 48
	v_readlane_b32 s100, v237, 42
	v_readlane_b32 s101, v237, 43
	v_min_i32_e32 v244, v244, v252
	v_min_i32_e32 v246, v246, v252
	v_min_i32_e32 v248, v248, v252
	v_min_i32_e32 v250, v250, v252
	v_mov_b32_e32 v245, 0
	v_mov_b32_e32 v247, 0
	v_mov_b32_e32 v249, 0
	v_mov_b32_e32 v251, 0
	v_mov_b32_e32 v254, v132
	v_mov_b32_e32 v255, 0
	v_lshlrev_b64 v[254:255], 17, v[254:255]
	v_lshl_add_u64 v[254:255], s[100:101], 0, v[254:255]
	v_lshl_add_u64 v[244:245], v[244:245], 2, v[254:255]
	v_lshl_add_u64 v[246:247], v[246:247], 2, v[254:255]
	v_lshl_add_u64 v[248:249], v[248:249], 2, v[254:255]
	v_lshl_add_u64 v[250:251], v[250:251], 2, v[254:255]
	global_load_dword v240, v[244:245], off
	global_load_dword v241, v[246:247], off
	global_load_dword v242, v[248:249], off
	global_load_dword v243, v[250:251], off
	v_readlane_b32 s100, v237, 44
	v_readlane_b32 s101, v237, 45
	s_and_b32 s98, s60, 4
	s_mov_b32 s99, 0
	s_waitcnt vmcnt(0)
	v_mov_b32_e32 v244, v240
	v_mov_b32_e32 v245, 0
	v_mov_b32_e32 v246, v241
	v_mov_b32_e32 v247, 0
	v_mov_b32_e32 v248, v242
	v_mov_b32_e32 v249, 0
	v_mov_b32_e32 v250, v243
	v_mov_b32_e32 v251, 0
	v_lshl_add_u64 v[244:245], v[244:245], 3, s[100:101]
	v_lshl_add_u64 v[246:247], v[246:247], 3, s[100:101]
	v_lshl_add_u64 v[248:249], v[248:249], 3, s[100:101]
	v_lshl_add_u64 v[250:251], v[250:251], 3, s[100:101]
	v_lshl_add_u64 v[244:245], v[244:245], 0, s[98:99]
	v_lshl_add_u64 v[246:247], v[246:247], 0, s[98:99]
	v_lshl_add_u64 v[248:249], v[248:249], 0, s[98:99]
	v_lshl_add_u64 v[250:251], v[250:251], 0, s[98:99]
	global_load_dword v252, v[244:245], off
	global_load_dword v253, v[246:247], off
	global_load_dword v254, v[248:249], off
	global_load_dword v255, v[250:251], off
	s_lshl_b32 s0, s60, 1
	v_and_or_b32 v130, s0, 6, v138
	v_lshlrev_b32_e32 v130, 5, v130
	v_lshlrev_b32_e32 v133, 2, v139
	v_add_u32_e32 v138, v156, v140
	s_and_b32 s8, s60, 7
	v_cmp_lt_i32_e32 vcc, v138, v141
	v_lshlrev_b32_e32 v130, 1, v130
	v_lshlrev_b32_e32 v136, 1, v133
	s_and_saveexec_b64 s[0:1], vcc
	s_cbranch_execz .LBB0_1849
	v_mov_b32_e32 v133, v131
	v_readlane_b32 s10, v237, 42
	v_lshlrev_b64 v[158:159], 17, v[132:133]
	v_readlane_b32 s11, v237, 43
	v_ashrrev_i32_e32 v139, 31, v138
	s_and_b32 s94, s8, 4
	v_lshl_add_u64 v[158:159], s[10:11], 0, v[158:159]
	v_lshl_add_u64 v[158:159], v[138:139], 2, v[158:159]
	v_readlane_b32 s10, v237, 44
	v_readlane_b32 s11, v237, 45
	v_mul_f32_e32 v133, 0xbfb8aa3b, v124
	v_mul_f32_e32 v139, 0xbfb8aa3b, v125
	v_mul_f32_e32 v157, 0xbfb8aa3b, v126
	v_mul_f32_e32 v160, 0xbfb8aa3b, v120
	v_mul_f32_e32 v161, 0xbfb8aa3b, v121
	v_mul_f32_e32 v162, 0xbfb8aa3b, v122
	v_mul_f32_e32 v163, 0xbfb8aa3b, v123
	v_exp_f32_e32 v133, v133
	v_exp_f32_e32 v164, v139
	v_exp_f32_e32 v157, v157
	v_exp_f32_e32 v160, v160
	v_exp_f32_e32 v161, v161
	v_exp_f32_e32 v162, v162
	v_exp_f32_e32 v163, v163
	v_add_f32_e32 v133, 1.0, v133
	v_add_f32_e32 v164, 1.0, v164
	v_add_f32_e32 v157, 1.0, v157
	v_add_f32_e32 v165, 1.0, v160
	v_add_f32_e32 v166, 1.0, v161
	v_add_f32_e32 v167, 1.0, v162
	v_add_f32_e32 v168, 1.0, v163
	v_rcp_f32_e32 v160, v133
	v_rcp_f32_e32 v161, v164
	v_rcp_f32_e32 v162, v157
	v_rcp_f32_e32 v164, v165
	v_rcp_f32_e32 v165, v166
	v_add_u32_e32 v138, v138, v142
	v_rcp_f32_e32 v166, v167
	v_rcp_f32_e32 v167, v168
	v_ashrrev_i32_e32 v139, 31, v138
	s_lshl_b32 s9, s8, 7
	v_lshlrev_b64 v[138:139], 10, v[138:139]
	v_lshl_add_u64 v[138:139], s[88:89], 0, v[138:139]
	v_pk_mul_f32 v[124:125], v[124:125], v[160:161]
	v_pk_mul_f32 v[120:121], v[120:121], v[164:165]
	v_pk_mul_f32 v[122:123], v[122:123], v[166:167]
	v_pk_mul_f32 v[116:117], v[124:125], v[116:117]
	v_pk_mul_f32 v[112:113], v[120:121], v[112:113]
	v_mov_b32_e32 v137, v131
	v_pk_mul_f32 v[114:115], v[122:123], v[114:115]
	v_ashrrev_i32_e32 v159, 31, v158
	v_lshl_add_u64 v[158:159], v[158:159], 3, s[10:11]
	v_lshl_add_u64 v[158:159], v[158:159], 0, s[94:95]
	v_mul_f32_e32 v159, 0xbfb8aa3b, v127
	v_exp_f32_e32 v159, v159
	s_and_b32 s94, s9, 0x200
	v_lshl_add_u64 v[120:121], v[138:139], 0, s[94:95]
	v_lshl_add_u64 v[120:121], v[120:121], 0, v[130:131]
	v_add_f32_e32 v159, 1.0, v159
	v_rcp_f32_e32 v163, v159
	v_lshl_add_u64 v[120:121], v[120:121], 0, v[136:137]
	v_pk_mul_f32 v[126:127], v[126:127], v[162:163]
	s_nop 0
	v_pk_mul_f32 v[118:119], v[126:127], v[118:119]
	s_waitcnt vmcnt(0)
	v_mov_b32_e32 v158, v252
	v_pk_mul_f32 v[116:117], v[116:117], v[158:159] op_sel_hi:[1,0]
	v_pk_mul_f32 v[118:119], v[118:119], v[158:159] op_sel_hi:[1,0]
	v_pk_mul_f32 v[112:113], v[112:113], v[158:159] op_sel_hi:[1,0]
	v_pk_mul_f32 v[114:115], v[114:115], v[158:159] op_sel_hi:[1,0]
	v_cvt_pk_bf16_f32 v116, v116, v117
	v_cvt_pk_bf16_f32 v117, v118, v119
	v_cvt_pk_bf16_f32 v112, v112, v113
	v_cvt_pk_bf16_f32 v113, v114, v115
	global_store_dwordx2 v[120:121], v[116:117], off
	global_store_dwordx2 v[120:121], v[112:113], off offset:32
.LBB0_1849:
	s_or_b64 exec, exec, s[0:1]
	v_add3_u32 v112, v140, v156, 16
	v_cmp_lt_i32_e32 vcc, v112, v141
	s_and_saveexec_b64 s[0:1], vcc
	s_cbranch_execz .LBB0_1851
	v_mov_b32_e32 v133, v131
	v_readlane_b32 s10, v237, 42
	v_lshlrev_b64 v[114:115], 17, v[132:133]
	v_readlane_b32 s11, v237, 43
	v_ashrrev_i32_e32 v113, 31, v112
	s_and_b32 s94, s8, 4
	v_lshl_add_u64 v[114:115], s[10:11], 0, v[114:115]
	v_lshl_add_u64 v[114:115], v[112:113], 2, v[114:115]
	v_readlane_b32 s10, v237, 44
	v_readlane_b32 s11, v237, 45
	v_mul_f32_e32 v113, 0xbfb8aa3b, v108
	v_mul_f32_e32 v116, 0xbfb8aa3b, v110
	v_mul_f32_e32 v117, 0xbfb8aa3b, v111
	v_mul_f32_e32 v118, 0xbfb8aa3b, v104
	v_mul_f32_e32 v119, 0xbfb8aa3b, v105
	v_mul_f32_e32 v120, 0xbfb8aa3b, v106
	v_mul_f32_e32 v121, 0xbfb8aa3b, v107
	v_exp_f32_e32 v122, v113
	v_exp_f32_e32 v116, v116
	v_exp_f32_e32 v117, v117
	v_exp_f32_e32 v118, v118
	v_exp_f32_e32 v119, v119
	v_exp_f32_e32 v120, v120
	v_exp_f32_e32 v121, v121
	v_add_f32_e32 v122, 1.0, v122
	v_add_f32_e32 v123, 1.0, v116
	v_add_f32_e32 v124, 1.0, v117
	v_add_f32_e32 v125, 1.0, v118
	v_add_f32_e32 v126, 1.0, v119
	v_add_f32_e32 v127, 1.0, v120
	v_add_f32_e32 v133, 1.0, v121
	v_rcp_f32_e32 v116, v122
	v_rcp_f32_e32 v118, v123
	v_rcp_f32_e32 v119, v124
	v_rcp_f32_e32 v120, v125
	v_rcp_f32_e32 v121, v126
	v_add_u32_e32 v112, v112, v142
	v_rcp_f32_e32 v122, v127
	v_rcp_f32_e32 v123, v133
	v_ashrrev_i32_e32 v113, 31, v112
	s_lshl_b32 s9, s8, 7
	v_lshlrev_b64 v[112:113], 10, v[112:113]
	v_lshl_add_u64 v[112:113], s[88:89], 0, v[112:113]
	v_pk_mul_f32 v[110:111], v[110:111], v[118:119]
	v_pk_mul_f32 v[104:105], v[104:105], v[120:121]
	v_pk_mul_f32 v[106:107], v[106:107], v[122:123]
	v_pk_mul_f32 v[102:103], v[110:111], v[102:103]
	v_pk_mul_f32 v[96:97], v[104:105], v[96:97]
	v_mov_b32_e32 v137, v131
	v_pk_mul_f32 v[98:99], v[106:107], v[98:99]
	v_ashrrev_i32_e32 v115, 31, v114
	v_lshl_add_u64 v[114:115], v[114:115], 3, s[10:11]
	v_lshl_add_u64 v[114:115], v[114:115], 0, s[94:95]
	v_mul_f32_e32 v115, 0xbfb8aa3b, v109
	v_exp_f32_e32 v115, v115
	s_and_b32 s94, s9, 0x200
	v_lshl_add_u64 v[104:105], v[112:113], 0, s[94:95]
	v_lshl_add_u64 v[104:105], v[104:105], 0, v[130:131]
	v_add_f32_e32 v115, 1.0, v115
	v_rcp_f32_e32 v117, v115
	v_lshl_add_u64 v[104:105], v[104:105], 0, v[136:137]
	v_pk_mul_f32 v[108:109], v[108:109], v[116:117]
	s_nop 0
	v_pk_mul_f32 v[100:101], v[108:109], v[100:101]
	v_mov_b32_e32 v114, v253
	v_pk_mul_f32 v[102:103], v[102:103], v[114:115] op_sel_hi:[1,0]
	v_pk_mul_f32 v[100:101], v[100:101], v[114:115] op_sel_hi:[1,0]
	v_pk_mul_f32 v[96:97], v[96:97], v[114:115] op_sel_hi:[1,0]
	v_pk_mul_f32 v[98:99], v[98:99], v[114:115] op_sel_hi:[1,0]
	v_cvt_pk_bf16_f32 v100, v100, v101
	v_cvt_pk_bf16_f32 v101, v102, v103
	v_cvt_pk_bf16_f32 v96, v96, v97
	v_cvt_pk_bf16_f32 v97, v98, v99
	global_store_dwordx2 v[104:105], v[100:101], off
	global_store_dwordx2 v[104:105], v[96:97], off offset:32
.LBB0_1851:
	s_or_b64 exec, exec, s[0:1]
	v_add3_u32 v96, v140, v156, 32
	v_cmp_lt_i32_e32 vcc, v96, v141
	s_and_saveexec_b64 s[0:1], vcc
	s_cbranch_execz .LBB0_1853
	v_mov_b32_e32 v133, v131
	v_readlane_b32 s10, v237, 42
	v_lshlrev_b64 v[98:99], 17, v[132:133]
	v_readlane_b32 s11, v237, 43
	v_ashrrev_i32_e32 v97, 31, v96
	s_and_b32 s94, s8, 4
	v_lshl_add_u64 v[98:99], s[10:11], 0, v[98:99]
	v_lshl_add_u64 v[98:99], v[96:97], 2, v[98:99]
	v_readlane_b32 s10, v237, 44
	v_readlane_b32 s11, v237, 45
	v_mul_f32_e32 v97, 0xbfb8aa3b, v92
	v_mul_f32_e32 v100, 0xbfb8aa3b, v94
	v_mul_f32_e32 v101, 0xbfb8aa3b, v95
	v_mul_f32_e32 v102, 0xbfb8aa3b, v88
	v_mul_f32_e32 v103, 0xbfb8aa3b, v89
	v_mul_f32_e32 v104, 0xbfb8aa3b, v90
	v_mul_f32_e32 v105, 0xbfb8aa3b, v91
	v_exp_f32_e32 v106, v97
	v_exp_f32_e32 v100, v100
	v_exp_f32_e32 v101, v101
	v_exp_f32_e32 v102, v102
	v_exp_f32_e32 v103, v103
	v_exp_f32_e32 v104, v104
	v_exp_f32_e32 v105, v105
	v_add_f32_e32 v106, 1.0, v106
	v_add_f32_e32 v107, 1.0, v100
	v_add_f32_e32 v108, 1.0, v101
	v_add_f32_e32 v109, 1.0, v102
	v_add_f32_e32 v110, 1.0, v103
	v_add_f32_e32 v111, 1.0, v104
	v_add_f32_e32 v112, 1.0, v105
	v_rcp_f32_e32 v100, v106
	v_rcp_f32_e32 v102, v107
	v_rcp_f32_e32 v103, v108
	v_rcp_f32_e32 v104, v109
	v_rcp_f32_e32 v105, v110
	v_add_u32_e32 v96, v96, v142
	v_rcp_f32_e32 v106, v111
	v_rcp_f32_e32 v107, v112
	v_ashrrev_i32_e32 v97, 31, v96
	s_lshl_b32 s9, s8, 7
	v_lshlrev_b64 v[96:97], 10, v[96:97]
	v_lshl_add_u64 v[96:97], s[88:89], 0, v[96:97]
	v_pk_mul_f32 v[94:95], v[94:95], v[102:103]
	v_pk_mul_f32 v[88:89], v[88:89], v[104:105]
	v_pk_mul_f32 v[90:91], v[90:91], v[106:107]
	v_pk_mul_f32 v[86:87], v[94:95], v[86:87]
	v_pk_mul_f32 v[80:81], v[88:89], v[80:81]
	v_mov_b32_e32 v137, v131
	v_pk_mul_f32 v[82:83], v[90:91], v[82:83]
	v_ashrrev_i32_e32 v99, 31, v98
	v_lshl_add_u64 v[98:99], v[98:99], 3, s[10:11]
	v_lshl_add_u64 v[98:99], v[98:99], 0, s[94:95]
	v_mul_f32_e32 v99, 0xbfb8aa3b, v93
	v_exp_f32_e32 v99, v99
	s_and_b32 s94, s9, 0x200
	v_lshl_add_u64 v[88:89], v[96:97], 0, s[94:95]
	v_lshl_add_u64 v[88:89], v[88:89], 0, v[130:131]
	v_add_f32_e32 v99, 1.0, v99
	v_rcp_f32_e32 v101, v99
	v_lshl_add_u64 v[88:89], v[88:89], 0, v[136:137]
	v_pk_mul_f32 v[92:93], v[92:93], v[100:101]
	s_nop 0
	v_pk_mul_f32 v[84:85], v[92:93], v[84:85]
	v_mov_b32_e32 v98, v254
	v_pk_mul_f32 v[86:87], v[86:87], v[98:99] op_sel_hi:[1,0]
	v_pk_mul_f32 v[84:85], v[84:85], v[98:99] op_sel_hi:[1,0]
	v_pk_mul_f32 v[80:81], v[80:81], v[98:99] op_sel_hi:[1,0]
	v_pk_mul_f32 v[82:83], v[82:83], v[98:99] op_sel_hi:[1,0]
	v_cvt_pk_bf16_f32 v84, v84, v85
	v_cvt_pk_bf16_f32 v85, v86, v87
	v_cvt_pk_bf16_f32 v80, v80, v81
	v_cvt_pk_bf16_f32 v81, v82, v83
	global_store_dwordx2 v[88:89], v[84:85], off
	global_store_dwordx2 v[88:89], v[80:81], off offset:32
.LBB0_1853:
	s_or_b64 exec, exec, s[0:1]
	v_add3_u32 v80, v140, v156, 48
	v_cmp_lt_i32_e32 vcc, v80, v141
	s_and_saveexec_b64 s[0:1], vcc
	s_cbranch_execz .LBB0_1855
	v_mov_b32_e32 v133, v131
	v_readlane_b32 s10, v237, 42
	v_lshlrev_b64 v[82:83], 17, v[132:133]
	v_readlane_b32 s11, v237, 43
	v_ashrrev_i32_e32 v81, 31, v80
	s_and_b32 s94, s8, 4
	v_lshl_add_u64 v[82:83], s[10:11], 0, v[82:83]
	v_lshl_add_u64 v[82:83], v[80:81], 2, v[82:83]
	v_readlane_b32 s10, v237, 44
	v_readlane_b32 s11, v237, 45
	v_mul_f32_e32 v81, 0xbfb8aa3b, v76
	v_mul_f32_e32 v84, 0xbfb8aa3b, v78
	v_mul_f32_e32 v85, 0xbfb8aa3b, v79
	v_mul_f32_e32 v86, 0xbfb8aa3b, v72
	v_mul_f32_e32 v87, 0xbfb8aa3b, v73
	v_mul_f32_e32 v88, 0xbfb8aa3b, v74
	v_mul_f32_e32 v89, 0xbfb8aa3b, v75
	v_exp_f32_e32 v90, v81
	v_exp_f32_e32 v84, v84
	v_exp_f32_e32 v85, v85
	v_exp_f32_e32 v86, v86
	v_exp_f32_e32 v87, v87
	v_exp_f32_e32 v88, v88
	v_exp_f32_e32 v89, v89
	v_add_f32_e32 v90, 1.0, v90
	v_add_f32_e32 v91, 1.0, v84
	v_add_f32_e32 v92, 1.0, v85
	v_add_f32_e32 v93, 1.0, v86
	v_add_f32_e32 v94, 1.0, v87
	v_add_f32_e32 v95, 1.0, v88
	v_add_f32_e32 v96, 1.0, v89
	v_rcp_f32_e32 v84, v90
	v_rcp_f32_e32 v86, v91
	v_rcp_f32_e32 v87, v92
	v_rcp_f32_e32 v88, v93
	v_rcp_f32_e32 v89, v94
	v_add_u32_e32 v80, v80, v142
	v_rcp_f32_e32 v90, v95
	v_rcp_f32_e32 v91, v96
	v_ashrrev_i32_e32 v81, 31, v80
	s_lshl_b32 s8, s8, 7
	v_lshlrev_b64 v[80:81], 10, v[80:81]
	v_lshl_add_u64 v[80:81], s[88:89], 0, v[80:81]
	v_pk_mul_f32 v[78:79], v[78:79], v[86:87]
	v_pk_mul_f32 v[72:73], v[72:73], v[88:89]
	v_pk_mul_f32 v[74:75], v[74:75], v[90:91]
	v_pk_mul_f32 v[70:71], v[78:79], v[70:71]
	v_pk_mul_f32 v[64:65], v[72:73], v[64:65]
	v_mov_b32_e32 v137, v131
	v_pk_mul_f32 v[66:67], v[74:75], v[66:67]
	v_ashrrev_i32_e32 v83, 31, v82
	v_lshl_add_u64 v[82:83], v[82:83], 3, s[10:11]
	v_lshl_add_u64 v[82:83], v[82:83], 0, s[94:95]
	v_mul_f32_e32 v83, 0xbfb8aa3b, v77
	v_exp_f32_e32 v83, v83
	s_and_b32 s94, s8, 0x200
	v_lshl_add_u64 v[72:73], v[80:81], 0, s[94:95]
	v_lshl_add_u64 v[72:73], v[72:73], 0, v[130:131]
	v_add_f32_e32 v83, 1.0, v83
	v_rcp_f32_e32 v85, v83
	v_lshl_add_u64 v[72:73], v[72:73], 0, v[136:137]
	v_pk_mul_f32 v[76:77], v[76:77], v[84:85]
	s_nop 0
	v_pk_mul_f32 v[68:69], v[76:77], v[68:69]
	v_mov_b32_e32 v82, v255
	v_pk_mul_f32 v[70:71], v[70:71], v[82:83] op_sel_hi:[1,0]
	v_pk_mul_f32 v[68:69], v[68:69], v[82:83] op_sel_hi:[1,0]
	v_pk_mul_f32 v[64:65], v[64:65], v[82:83] op_sel_hi:[1,0]
	v_pk_mul_f32 v[66:67], v[66:67], v[82:83] op_sel_hi:[1,0]
	v_cvt_pk_bf16_f32 v68, v68, v69
	v_cvt_pk_bf16_f32 v69, v70, v71
	v_cvt_pk_bf16_f32 v64, v64, v65
	v_cvt_pk_bf16_f32 v65, v66, v67
	global_store_dwordx2 v[72:73], v[68:69], off
	global_store_dwordx2 v[72:73], v[64:65], off offset:32
	s_or_b64 exec, exec, s[0:1]
	s_andn2_b64 vcc, exec, s[6:7]
	s_cbranch_vccnz .LBB0_1797
	s_branch .LBB0_1856

.LBB0_1987:
	v_add_u32_e32 v252, -1, v139
	v_add_u32_e32 v244, v138, v154
	v_add3_u32 v246, v138, v154, 16
	v_add3_u32 v248, v138, v154, 32
	v_add3_u32 v250, v138, v154, 48
	v_readlane_b32 s100, v237, 42
	v_readlane_b32 s101, v237, 43
	v_min_i32_e32 v244, v244, v252
	v_min_i32_e32 v246, v246, v252
	v_min_i32_e32 v248, v248, v252
	v_min_i32_e32 v250, v250, v252
	v_mov_b32_e32 v245, 0
	v_mov_b32_e32 v247, 0
	v_mov_b32_e32 v249, 0
	v_mov_b32_e32 v251, 0
	v_mov_b32_e32 v254, v130
	v_mov_b32_e32 v255, 0
	v_lshlrev_b64 v[254:255], 17, v[254:255]
	v_lshl_add_u64 v[254:255], s[100:101], 0, v[254:255]
	v_lshl_add_u64 v[244:245], v[244:245], 2, v[254:255]
	v_lshl_add_u64 v[246:247], v[246:247], 2, v[254:255]
	v_lshl_add_u64 v[248:249], v[248:249], 2, v[254:255]
	v_lshl_add_u64 v[250:251], v[250:251], 2, v[254:255]
	global_load_dword v240, v[244:245], off
	global_load_dword v241, v[246:247], off
	global_load_dword v242, v[248:249], off
	global_load_dword v243, v[250:251], off
	v_and_b32_e32 v131, 64, v131
	v_readlane_b32 s0, v237, 31
	v_lshlrev_b32_e32 v134, 2, v159
	v_add_u32_e32 v136, v154, v138
	v_readlane_b32 s1, v237, 32
	s_and_b32 s10, s0, 7
	v_cmp_lt_i32_e32 vcc, v136, v139
	v_lshlrev_b32_e32 v132, 1, v131
	v_lshlrev_b32_e32 v134, 1, v134
	s_and_saveexec_b64 s[0:1], vcc
	s_cbranch_execz .LBB0_1989
	v_mov_b32_e32 v131, v133
	v_readlane_b32 s12, v237, 42
	v_lshlrev_b64 v[148:149], 17, v[130:131]
	v_readlane_b32 s13, v237, 43
	v_ashrrev_i32_e32 v137, 31, v136
	v_cvt_pk_bf16_f32 v112, v112, v113
	v_lshl_add_u64 v[148:149], s[12:13], 0, v[148:149]
	v_lshl_add_u64 v[136:137], v[136:137], 2, v[148:149]
	v_readlane_b32 s12, v237, 40
	v_cvt_pk_bf16_f32 v113, v114, v115
	v_readlane_b32 s13, v237, 41
	s_lshl_b32 s92, s10, 8
	v_mov_b32_e32 v135, v133
	v_cvt_pk_bf16_f32 v124, v124, v125
	v_cvt_pk_bf16_f32 v125, v126, v127
	v_cvt_pk_bf16_f32 v120, v120, v121
	v_cvt_pk_bf16_f32 v121, v122, v123
	v_cvt_pk_bf16_f32 v116, v116, v117
	v_cvt_pk_bf16_f32 v117, v118, v119
	s_waitcnt vmcnt(0)
	v_mov_b32_e32 v136, v240
	v_ashrrev_i32_e32 v137, 31, v136
	v_lshlrev_b64 v[114:115], 11, v[136:137]
	v_lshl_add_u64 v[114:115], s[12:13], 0, v[114:115]
	v_lshl_add_u64 v[114:115], v[114:115], 0, s[92:93]
	v_lshl_add_u64 v[114:115], v[114:115], 0, v[132:133]
	v_lshl_add_u64 v[114:115], v[114:115], 0, v[134:135]
	global_store_dwordx2 v[114:115], v[124:125], off
	global_store_dwordx2 v[114:115], v[120:121], off offset:32
	global_store_dwordx2 v[114:115], v[116:117], off offset:64
	global_store_dwordx2 v[114:115], v[112:113], off offset:96
.LBB0_1989:
	s_or_b64 exec, exec, s[0:1]
	v_add3_u32 v112, v138, v154, 16
	v_cmp_lt_i32_e32 vcc, v112, v139
	s_and_saveexec_b64 s[0:1], vcc
	s_cbranch_execz .LBB0_1991
	v_mov_b32_e32 v131, v133
	v_readlane_b32 s12, v237, 42
	v_lshlrev_b64 v[114:115], 17, v[130:131]
	v_readlane_b32 s13, v237, 43
	v_ashrrev_i32_e32 v113, 31, v112
	v_cvt_pk_bf16_f32 v96, v96, v97
	v_lshl_add_u64 v[114:115], s[12:13], 0, v[114:115]
	v_lshl_add_u64 v[112:113], v[112:113], 2, v[114:115]
	v_readlane_b32 s12, v237, 40
	v_cvt_pk_bf16_f32 v97, v98, v99
	v_readlane_b32 s13, v237, 41
	s_lshl_b32 s92, s10, 8
	v_mov_b32_e32 v135, v133
	v_cvt_pk_bf16_f32 v108, v108, v109
	v_cvt_pk_bf16_f32 v109, v110, v111
	v_cvt_pk_bf16_f32 v104, v104, v105
	v_cvt_pk_bf16_f32 v105, v106, v107
	v_cvt_pk_bf16_f32 v100, v100, v101
	v_cvt_pk_bf16_f32 v101, v102, v103
	v_mov_b32_e32 v112, v241
	v_ashrrev_i32_e32 v113, 31, v112
	v_lshlrev_b64 v[98:99], 11, v[112:113]
	v_lshl_add_u64 v[98:99], s[12:13], 0, v[98:99]
	v_lshl_add_u64 v[98:99], v[98:99], 0, s[92:93]
	v_lshl_add_u64 v[98:99], v[98:99], 0, v[132:133]
	v_lshl_add_u64 v[98:99], v[98:99], 0, v[134:135]
	global_store_dwordx2 v[98:99], v[108:109], off
	global_store_dwordx2 v[98:99], v[104:105], off offset:32
	global_store_dwordx2 v[98:99], v[100:101], off offset:64
	global_store_dwordx2 v[98:99], v[96:97], off offset:96
.LBB0_1991:
	s_or_b64 exec, exec, s[0:1]
	v_add3_u32 v96, v138, v154, 32
	v_cmp_lt_i32_e32 vcc, v96, v139
	s_and_saveexec_b64 s[0:1], vcc
	s_cbranch_execz .LBB0_1993
	v_mov_b32_e32 v131, v133
	v_readlane_b32 s12, v237, 42
	v_lshlrev_b64 v[98:99], 17, v[130:131]
	v_readlane_b32 s13, v237, 43
	v_ashrrev_i32_e32 v97, 31, v96
	v_cvt_pk_bf16_f32 v80, v80, v81
	v_lshl_add_u64 v[98:99], s[12:13], 0, v[98:99]
	v_lshl_add_u64 v[96:97], v[96:97], 2, v[98:99]
	v_readlane_b32 s12, v237, 40
	v_cvt_pk_bf16_f32 v81, v82, v83
	v_readlane_b32 s13, v237, 41
	s_lshl_b32 s92, s10, 8
	v_mov_b32_e32 v135, v133
	v_cvt_pk_bf16_f32 v92, v92, v93
	v_cvt_pk_bf16_f32 v93, v94, v95
	v_cvt_pk_bf16_f32 v88, v88, v89
	v_cvt_pk_bf16_f32 v89, v90, v91
	v_cvt_pk_bf16_f32 v84, v84, v85
	v_cvt_pk_bf16_f32 v85, v86, v87
	v_mov_b32_e32 v96, v242
	v_ashrrev_i32_e32 v97, 31, v96
	v_lshlrev_b64 v[82:83], 11, v[96:97]
	v_lshl_add_u64 v[82:83], s[12:13], 0, v[82:83]
	v_lshl_add_u64 v[82:83], v[82:83], 0, s[92:93]
	v_lshl_add_u64 v[82:83], v[82:83], 0, v[132:133]
	v_lshl_add_u64 v[82:83], v[82:83], 0, v[134:135]
	global_store_dwordx2 v[82:83], v[92:93], off
	global_store_dwordx2 v[82:83], v[88:89], off offset:32
	global_store_dwordx2 v[82:83], v[84:85], off offset:64
	global_store_dwordx2 v[82:83], v[80:81], off offset:96
.LBB0_1993:
	s_or_b64 exec, exec, s[0:1]
	v_add3_u32 v80, v138, v154, 48
	v_cmp_lt_i32_e32 vcc, v80, v139
	s_and_saveexec_b64 s[0:1], vcc
	s_cbranch_execz .LBB0_1995
	v_mov_b32_e32 v131, v133
	v_readlane_b32 s12, v237, 42
	v_lshlrev_b64 v[82:83], 17, v[130:131]
	v_readlane_b32 s13, v237, 43
	v_ashrrev_i32_e32 v81, 31, v80
	s_lshl_b32 s92, s10, 8
	v_lshl_add_u64 v[82:83], s[12:13], 0, v[82:83]
	v_lshl_add_u64 v[80:81], v[80:81], 2, v[82:83]
	v_readlane_b32 s10, v237, 40
	v_cvt_pk_bf16_f32 v64, v64, v65
	v_cvt_pk_bf16_f32 v65, v66, v67
	v_readlane_b32 s11, v237, 41
	v_mov_b32_e32 v135, v133
	v_cvt_pk_bf16_f32 v76, v76, v77
	v_cvt_pk_bf16_f32 v77, v78, v79
	v_cvt_pk_bf16_f32 v72, v72, v73
	v_cvt_pk_bf16_f32 v73, v74, v75
	v_cvt_pk_bf16_f32 v68, v68, v69
	v_cvt_pk_bf16_f32 v69, v70, v71
	v_mov_b32_e32 v80, v243
	v_ashrrev_i32_e32 v81, 31, v80
	v_lshlrev_b64 v[66:67], 11, v[80:81]
	v_lshl_add_u64 v[66:67], s[10:11], 0, v[66:67]
	v_lshl_add_u64 v[66:67], v[66:67], 0, s[92:93]
	v_lshl_add_u64 v[66:67], v[66:67], 0, v[132:133]
	v_lshl_add_u64 v[66:67], v[66:67], 0, v[134:135]
	global_store_dwordx2 v[66:67], v[76:77], off
	global_store_dwordx2 v[66:67], v[72:73], off offset:32
	global_store_dwordx2 v[66:67], v[68:69], off offset:64
	global_store_dwordx2 v[66:67], v[64:65], off offset:96
	s_or_b64 exec, exec, s[0:1]
	s_andn2_b64 vcc, exec, s[6:7]
	s_cbranch_vccnz .LBB0_1937
	s_branch .LBB0_1996
